# GIN main loop: hipcc's per-iteration vmcnt(0) at the loop top (drained every in-flight LDS-DMA each iteration; GUP/GDOWN loops have none) moved out of the K-loop to once per tile
# baseline (speedup 1.0000x reference)
.Lzskip_gin:
	v_mov_b64_e32 v[18:19], 0
	v_mov_b64_e32 v[20:21], 0
	v_mov_b64_e32 v[22:23], 0
	v_mov_b64_e32 v[24:25], 0
	v_mov_b64_e32 v[26:27], 0
	v_mov_b64_e32 v[28:29], 0
	v_mov_b64_e32 v[30:31], 0
	v_mov_b64_e32 v[32:33], 0
	v_mov_b64_e32 v[34:35], 0
	v_mov_b64_e32 v[36:37], 0
	v_mov_b64_e32 v[38:39], 0
	v_mov_b64_e32 v[40:41], 0
	v_mov_b64_e32 v[42:43], 0
	v_mov_b64_e32 v[44:45], 0
	v_mov_b64_e32 v[46:47], 0
	v_mov_b64_e32 v[48:49], 0
	v_mov_b64_e32 v[50:51], 0
	v_mov_b64_e32 v[52:53], 0
	v_mov_b64_e32 v[54:55], 0
	v_mov_b64_e32 v[56:57], 0
	v_mov_b64_e32 v[58:59], 0
	v_mov_b64_e32 v[60:61], 0
	s_branch .LBB0_74
	s_nop 0
	s_nop 0
	s_nop 0
	s_nop 0
	s_nop 0
	s_nop 0
	s_nop 0
	s_nop 0
	s_nop 0
	s_nop 0
	s_nop 0
	s_nop 0
	s_nop 0
	s_nop 0
	s_nop 0
	s_nop 0
	s_nop 0
	s_nop 0
	s_nop 0
	s_nop 0
.LBB0_70:
	s_mov_b64 s[38:39], 0

.LBB0_74:
	s_ashr_i32 s63, s62, 31
	v_mov_b64_e32 v[62:63], 0
	s_lshl_b64 s[68:69], s[62:63], 19
	v_mov_b64_e32 v[64:65], 0
	s_add_u32 s76, s36, s68
	v_mov_b64_e32 v[66:67], 0
	s_addc_u32 s77, s37, s69
	v_mov_b64_e32 v[68:69], 0
	s_and_b64 s[68:69], s[38:39], exec
	v_mov_b64_e32 v[70:71], 0
	s_cselect_b32 s2, s77, s91
	v_mov_b64_e32 v[72:73], 0
	s_cselect_b32 s6, s76, s90
	v_mov_b64_e32 v[74:75], 0
	s_ashr_i32 s51, s50, 31
	v_mov_b64_e32 v[76:77], 0
	s_lshl_b64 s[68:69], s[50:51], 19
	v_mov_b64_e32 v[78:79], 0
	s_add_u32 s78, s42, s68
	v_mov_b64_e32 v[80:81], 0
	s_addc_u32 s79, s43, s69
	v_mov_b64_e32 v[82:83], 0
	s_and_b64 s[68:69], s[38:39], exec
	v_mov_b64_e32 v[84:85], 0
	s_cselect_b32 s51, s79, s93
	v_mov_b64_e32 v[86:87], 0
	s_cselect_b32 s63, s78, s92
	v_mov_b64_e32 v[88:89], 0
	s_add_u32 s90, s90, 0x40080
	v_mov_b64_e32 v[90:91], 0
	s_addc_u32 s91, s91, 0
	v_mov_b64_e32 v[92:93], 0
	s_add_u32 s89, s92, 0x100
	v_mov_b64_e32 v[94:95], 0
	v_mov_b64_e32 v[2:3], 0
	v_mov_b64_e32 v[96:97], 0
	v_mov_b64_e32 v[98:99], 0
	v_mov_b64_e32 v[100:101], 0
	v_mov_b64_e32 v[102:103], 0
	v_mov_b64_e32 v[104:105], 0
	v_mov_b64_e32 v[106:107], 0
	v_mov_b64_e32 v[108:109], 0
	v_mov_b64_e32 v[110:111], 0
	v_mov_b64_e32 v[112:113], 0
	v_mov_b64_e32 v[114:115], 0
	v_mov_b64_e32 v[116:117], 0
	v_mov_b64_e32 v[118:119], 0
	v_mov_b64_e32 v[120:121], 0
	v_mov_b64_e32 v[122:123], 0
	v_mov_b64_e32 v[124:125], 0
	v_mov_b64_e32 v[126:127], 0
	v_mov_b64_e32 v[128:129], 0
	s_addc_u32 s96, s93, 0
	s_mov_b32 s97, -2
	s_waitcnt vmcnt(0)
.LBB0_75:
	s_add_u32 s68, s90, 0xfffc0080
	s_addc_u32 s69, s91, -1
	s_add_i32 s70, 0, 0x10000
	s_cmp_eq_u32 s97, 12
	s_cselect_b32 s95, s2, s69
	s_cselect_b32 s94, s6, s68
	v_add_u32_e32 v140, s70, v151
	s_cselect_b32 s93, s51, s96
	s_cselect_b32 s92, s63, s89
	s_add_i32 s71, 0, 0x14000
	ds_read_b128 v[154:157], v140
	ds_read_b128 v[158:161], v140 offset:1024
	ds_read_b128 v[162:165], v140 offset:2048
	ds_read_b128 v[166:169], v140 offset:3072
	v_add_u32_e32 v140, s71, v151
	ds_read_b128 v[170:173], v140
	ds_read_b128 v[174:177], v140 offset:1024
	ds_read_b128 v[178:181], v140 offset:2048
	ds_read_b128 v[182:185], v140 offset:3072
	v_lshl_add_u64 v[140:141], s[90:91], 0, v[136:137]
	s_add_i32 m0, s18, 0xc000
	ds_read_b128 v[186:189], v153
	ds_read_b128 v[190:193], v153 offset:1024
	ds_read_b128 v[194:197], v153 offset:2048
	ds_read_b128 v[198:201], v153 offset:3072
	ds_read_b128 v[202:205], v153 offset:4096
	ds_read_b128 v[210:213], v153 offset:5120
	ds_read_b128 v[214:217], v153 offset:6144
	ds_read_b128 v[218:221], v153 offset:7168
	global_load_lds_dwordx4 v[140:141], off
	v_lshl_add_u64 v[140:141], s[90:91], 0, v[138:139]
	s_add_i32 m0, s18, 0xe000
	s_nop 0
	global_load_lds_dwordx4 v[140:141], off
	s_waitcnt vmcnt(8)
	s_waitcnt lgkmcnt(0)
	s_barrier
	s_waitcnt lgkmcnt(0)
	v_mfma_f32_16x16x32_bf16 v[126:129], v[154:157], v[186:189], v[126:129]
	v_mfma_f32_16x16x32_bf16 v[122:125], v[162:165], v[186:189], v[122:125]
	v_mfma_f32_16x16x32_bf16 v[110:113], v[154:157], v[194:197], v[110:113]
	v_mfma_f32_16x16x32_bf16 v[106:109], v[162:165], v[194:197], v[106:109]
	v_mfma_f32_16x16x32_bf16 v[98:101], v[154:157], v[202:205], v[98:101]
	v_mfma_f32_16x16x32_bf16 v[90:93], v[162:165], v[202:205], v[90:93]
	v_mfma_f32_16x16x32_bf16 v[82:85], v[154:157], v[214:217], v[82:85]
	v_mfma_f32_16x16x32_bf16 v[74:77], v[162:165], v[214:217], v[74:77]
	v_mfma_f32_16x16x32_bf16 v[118:121], v[170:173], v[186:189], v[118:121]
	v_mfma_f32_16x16x32_bf16 v[114:117], v[178:181], v[186:189], v[114:117]
	v_mfma_f32_16x16x32_bf16 v[102:105], v[170:173], v[194:197], v[102:105]
	v_mfma_f32_16x16x32_bf16 v[94:97], v[178:181], v[194:197], v[94:97]
	v_mfma_f32_16x16x32_bf16 v[86:89], v[170:173], v[202:205], v[86:89]
	v_mfma_f32_16x16x32_bf16 v[78:81], v[178:181], v[202:205], v[78:81]
	v_mfma_f32_16x16x32_bf16 v[70:73], v[170:173], v[214:217], v[70:73]
	v_mfma_f32_16x16x32_bf16 v[66:69], v[178:181], v[214:217], v[66:69]
	v_mfma_f32_16x16x32_bf16 v[126:129], v[158:161], v[190:193], v[126:129]
	v_mfma_f32_16x16x32_bf16 v[122:125], v[166:169], v[190:193], v[122:125]
	v_mfma_f32_16x16x32_bf16 v[110:113], v[158:161], v[198:201], v[110:113]
	v_mfma_f32_16x16x32_bf16 v[106:109], v[166:169], v[198:201], v[106:109]
	v_mfma_f32_16x16x32_bf16 v[98:101], v[158:161], v[210:213], v[98:101]
	v_mfma_f32_16x16x32_bf16 v[90:93], v[166:169], v[210:213], v[90:93]
	v_mfma_f32_16x16x32_bf16 v[82:85], v[158:161], v[218:221], v[82:85]
	v_mfma_f32_16x16x32_bf16 v[74:77], v[166:169], v[218:221], v[74:77]
	v_mfma_f32_16x16x32_bf16 v[118:121], v[174:177], v[190:193], v[118:121]
	v_mfma_f32_16x16x32_bf16 v[114:117], v[182:185], v[190:193], v[114:117]
	v_mfma_f32_16x16x32_bf16 v[102:105], v[174:177], v[198:201], v[102:105]
	v_mfma_f32_16x16x32_bf16 v[94:97], v[182:185], v[198:201], v[94:97]
	v_mfma_f32_16x16x32_bf16 v[86:89], v[174:177], v[210:213], v[86:89]
	v_mfma_f32_16x16x32_bf16 v[78:81], v[182:185], v[210:213], v[78:81]
	v_mfma_f32_16x16x32_bf16 v[70:73], v[174:177], v[218:221], v[70:73]
	v_mfma_f32_16x16x32_bf16 v[66:69], v[182:185], v[218:221], v[66:69]
	s_barrier
	s_add_i32 s68, s70, s16
	v_lshl_add_u64 v[140:141], s[92:93], 0, v[0:1]
	s_mov_b32 m0, s68
	ds_read_b128 v[186:189], v153 offset:16384
	ds_read_b128 v[190:193], v153 offset:17408
	ds_read_b128 v[194:197], v153 offset:18432
	ds_read_b128 v[198:201], v153 offset:19456
	ds_read_b128 v[202:205], v153 offset:20480
	ds_read_b128 v[210:213], v153 offset:21504
	ds_read_b128 v[214:217], v153 offset:22528
	ds_read_b128 v[218:221], v153 offset:23552
	global_load_lds_dwordx4 v[140:141], off
	s_add_i32 m0, s68, 0x2000
	s_add_u32 s68, s92, 0x40000
	v_lshl_add_u64 v[144:145], s[92:93], 0, v[130:131]
	s_addc_u32 s69, s93, 0
	s_add_i32 s70, s71, s16
	global_load_lds_dwordx4 v[144:145], off
	v_lshl_add_u64 v[148:149], s[68:69], 0, v[0:1]
	s_mov_b32 m0, s70
	v_lshl_add_u64 v[206:207], s[94:95], 0, v[132:133]
	global_load_lds_dwordx4 v[148:149], off
	v_lshl_add_u64 v[148:149], s[68:69], 0, v[130:131]
	s_add_i32 m0, s70, 0x2000
	s_nop 0
	global_load_lds_dwordx4 v[148:149], off
	v_lshl_add_u64 v[148:149], s[94:95], 0, v[134:135]
	s_mov_b32 m0, s18
	s_nop 0
	global_load_lds_dwordx4 v[148:149], off
	s_mov_b32 m0, s19
	s_nop 0
	global_load_lds_dwordx4 v[206:207], off
	s_waitcnt vmcnt(8)
	s_waitcnt lgkmcnt(0)
	s_barrier
	s_waitcnt lgkmcnt(0)
	v_mfma_f32_16x16x32_bf16 v[62:65], v[154:157], v[186:189], v[62:65]
	v_mfma_f32_16x16x32_bf16 v[58:61], v[162:165], v[186:189], v[58:61]
	v_mfma_f32_16x16x32_bf16 v[50:53], v[154:157], v[194:197], v[50:53]
	v_mfma_f32_16x16x32_bf16 v[42:45], v[162:165], v[194:197], v[42:45]
	v_mfma_f32_16x16x32_bf16 v[34:37], v[154:157], v[202:205], v[34:37]
	v_mfma_f32_16x16x32_bf16 v[26:29], v[162:165], v[202:205], v[26:29]
	v_mfma_f32_16x16x32_bf16 v[18:21], v[154:157], v[214:217], v[18:21]
	v_mfma_f32_16x16x32_bf16 v[10:13], v[162:165], v[214:217], v[10:13]
	v_mfma_f32_16x16x32_bf16 v[54:57], v[170:173], v[186:189], v[54:57]
	v_mfma_f32_16x16x32_bf16 v[46:49], v[178:181], v[186:189], v[46:49]
	v_mfma_f32_16x16x32_bf16 v[38:41], v[170:173], v[194:197], v[38:41]
	v_mfma_f32_16x16x32_bf16 v[30:33], v[178:181], v[194:197], v[30:33]
	v_mfma_f32_16x16x32_bf16 v[22:25], v[170:173], v[202:205], v[22:25]
	v_mfma_f32_16x16x32_bf16 v[14:17], v[178:181], v[202:205], v[14:17]
	v_mfma_f32_16x16x32_bf16 v[6:9], v[170:173], v[214:217], v[6:9]
	v_mfma_f32_16x16x32_bf16 v[2:5], v[178:181], v[214:217], v[2:5]
	v_mfma_f32_16x16x32_bf16 v[62:65], v[158:161], v[190:193], v[62:65]
	v_mfma_f32_16x16x32_bf16 v[58:61], v[166:169], v[190:193], v[58:61]
	v_mfma_f32_16x16x32_bf16 v[50:53], v[158:161], v[198:201], v[50:53]
	v_mfma_f32_16x16x32_bf16 v[42:45], v[166:169], v[198:201], v[42:45]
	v_mfma_f32_16x16x32_bf16 v[34:37], v[158:161], v[210:213], v[34:37]
	v_mfma_f32_16x16x32_bf16 v[26:29], v[166:169], v[210:213], v[26:29]
	v_mfma_f32_16x16x32_bf16 v[18:21], v[158:161], v[218:221], v[18:21]
	v_mfma_f32_16x16x32_bf16 v[10:13], v[166:169], v[218:221], v[10:13]
	v_mfma_f32_16x16x32_bf16 v[54:57], v[174:177], v[190:193], v[54:57]
	v_mfma_f32_16x16x32_bf16 v[46:49], v[182:185], v[190:193], v[46:49]
	v_mfma_f32_16x16x32_bf16 v[38:41], v[174:177], v[198:201], v[38:41]
	v_mfma_f32_16x16x32_bf16 v[30:33], v[182:185], v[198:201], v[30:33]
	v_mfma_f32_16x16x32_bf16 v[22:25], v[174:177], v[210:213], v[22:25]
	v_mfma_f32_16x16x32_bf16 v[14:17], v[182:185], v[210:213], v[14:17]
	v_mfma_f32_16x16x32_bf16 v[6:9], v[174:177], v[218:221], v[6:9]
	v_mfma_f32_16x16x32_bf16 v[2:5], v[182:185], v[218:221], v[2:5]
	s_barrier
	s_add_i32 s70, 0, 0x18000
	v_add_u32_e32 v142, s70, v151
	s_add_i32 s71, 0, 0x1c000
	ds_read_b128 v[154:157], v142
	ds_read_b128 v[158:161], v142 offset:1024
	ds_read_b128 v[162:165], v142 offset:2048
	ds_read_b128 v[166:169], v142 offset:3072
	v_add_u32_e32 v142, s71, v151
	ds_read_b128 v[170:173], v142
	ds_read_b128 v[174:177], v142 offset:1024
	ds_read_b128 v[178:181], v142 offset:2048
	ds_read_b128 v[182:185], v142 offset:3072
	s_add_u32 s68, s94, 0x40000
	s_addc_u32 s69, s95, 0
	s_mov_b32 m0, s20
	v_lshl_add_u64 v[222:223], s[68:69], 0, v[134:135]
	ds_read_b128 v[186:189], v153 offset:32768
	ds_read_b128 v[190:193], v153 offset:33792
	ds_read_b128 v[194:197], v153 offset:34816
	ds_read_b128 v[198:201], v153 offset:35840
	ds_read_b128 v[202:205], v153 offset:36864
	ds_read_b128 v[210:213], v153 offset:37888
	ds_read_b128 v[214:217], v153 offset:38912
	ds_read_b128 v[218:221], v153 offset:39936
	global_load_lds_dwordx4 v[222:223], off
	v_lshl_add_u64 v[222:223], s[68:69], 0, v[132:133]
	s_mov_b32 m0, s21
	s_nop 0
	global_load_lds_dwordx4 v[222:223], off
	s_waitcnt vmcnt(8)
	s_waitcnt lgkmcnt(0)
	s_barrier
	s_waitcnt lgkmcnt(0)
	v_mfma_f32_16x16x32_bf16 v[126:129], v[154:157], v[186:189], v[126:129]
	v_mfma_f32_16x16x32_bf16 v[122:125], v[162:165], v[186:189], v[122:125]
	v_mfma_f32_16x16x32_bf16 v[110:113], v[154:157], v[194:197], v[110:113]
	v_mfma_f32_16x16x32_bf16 v[106:109], v[162:165], v[194:197], v[106:109]
	v_mfma_f32_16x16x32_bf16 v[98:101], v[154:157], v[202:205], v[98:101]
	v_mfma_f32_16x16x32_bf16 v[90:93], v[162:165], v[202:205], v[90:93]
	v_mfma_f32_16x16x32_bf16 v[82:85], v[154:157], v[214:217], v[82:85]
	v_mfma_f32_16x16x32_bf16 v[74:77], v[162:165], v[214:217], v[74:77]
	v_mfma_f32_16x16x32_bf16 v[118:121], v[170:173], v[186:189], v[118:121]
	v_mfma_f32_16x16x32_bf16 v[114:117], v[178:181], v[186:189], v[114:117]
	v_mfma_f32_16x16x32_bf16 v[102:105], v[170:173], v[194:197], v[102:105]
	v_mfma_f32_16x16x32_bf16 v[94:97], v[178:181], v[194:197], v[94:97]
	v_mfma_f32_16x16x32_bf16 v[86:89], v[170:173], v[202:205], v[86:89]
	v_mfma_f32_16x16x32_bf16 v[78:81], v[178:181], v[202:205], v[78:81]
	v_mfma_f32_16x16x32_bf16 v[70:73], v[170:173], v[214:217], v[70:73]
	v_mfma_f32_16x16x32_bf16 v[66:69], v[178:181], v[214:217], v[66:69]
	v_mfma_f32_16x16x32_bf16 v[126:129], v[158:161], v[190:193], v[126:129]
	v_mfma_f32_16x16x32_bf16 v[122:125], v[166:169], v[190:193], v[122:125]
	v_mfma_f32_16x16x32_bf16 v[110:113], v[158:161], v[198:201], v[110:113]
	v_mfma_f32_16x16x32_bf16 v[106:109], v[166:169], v[198:201], v[106:109]
	v_mfma_f32_16x16x32_bf16 v[98:101], v[158:161], v[210:213], v[98:101]
	v_mfma_f32_16x16x32_bf16 v[90:93], v[166:169], v[210:213], v[90:93]
	v_mfma_f32_16x16x32_bf16 v[82:85], v[158:161], v[218:221], v[82:85]
	v_mfma_f32_16x16x32_bf16 v[74:77], v[166:169], v[218:221], v[74:77]
	v_mfma_f32_16x16x32_bf16 v[118:121], v[174:177], v[190:193], v[118:121]
	v_mfma_f32_16x16x32_bf16 v[114:117], v[182:185], v[190:193], v[114:117]
	v_mfma_f32_16x16x32_bf16 v[102:105], v[174:177], v[198:201], v[102:105]
	v_mfma_f32_16x16x32_bf16 v[94:97], v[182:185], v[198:201], v[94:97]
	v_mfma_f32_16x16x32_bf16 v[86:89], v[174:177], v[210:213], v[86:89]
	v_mfma_f32_16x16x32_bf16 v[78:81], v[182:185], v[210:213], v[78:81]
	v_mfma_f32_16x16x32_bf16 v[70:73], v[174:177], v[218:221], v[70:73]
	v_mfma_f32_16x16x32_bf16 v[66:69], v[182:185], v[218:221], v[66:69]
	s_barrier
	s_add_i32 s68, s70, s16
	v_lshl_add_u64 v[140:141], v[140:141], 0, s[34:35]
	s_mov_b32 m0, s68
	ds_read_b128 v[186:189], v153 offset:49152
	ds_read_b128 v[190:193], v153 offset:50176
	ds_read_b128 v[194:197], v153 offset:51200
	ds_read_b128 v[198:201], v153 offset:52224
	ds_read_b128 v[202:205], v153 offset:53248
	ds_read_b128 v[210:213], v153 offset:54272
	ds_read_b128 v[214:217], v153 offset:55296
	ds_read_b128 v[218:221], v153 offset:56320
	global_load_lds_dwordx4 v[140:141], off
	s_add_i32 m0, s68, 0x2000
	s_add_u32 s68, s92, 0x40080
	v_lshl_add_u64 v[140:141], v[144:145], 0, s[34:35]
	s_addc_u32 s69, s93, 0
	s_add_i32 s70, s71, s16
	global_load_lds_dwordx4 v[140:141], off
	v_lshl_add_u64 v[140:141], s[68:69], 0, v[0:1]
	s_mov_b32 m0, s70
	s_nop 0
	global_load_lds_dwordx4 v[140:141], off
	v_lshl_add_u64 v[140:141], s[68:69], 0, v[130:131]
	s_add_i32 m0, s70, 0x2000
	s_nop 0
	global_load_lds_dwordx4 v[140:141], off
	v_lshl_add_u64 v[140:141], v[148:149], 0, s[34:35]
	s_mov_b32 m0, s23
	s_nop 0
	global_load_lds_dwordx4 v[140:141], off
	v_lshl_add_u64 v[140:141], v[206:207], 0, s[34:35]
	s_mov_b32 m0, s29
	s_nop 0
	global_load_lds_dwordx4 v[140:141], off
	s_waitcnt vmcnt(8)
	s_waitcnt lgkmcnt(0)
	s_barrier
	s_waitcnt lgkmcnt(0)
	v_mfma_f32_16x16x32_bf16 v[62:65], v[154:157], v[186:189], v[62:65]
	v_mfma_f32_16x16x32_bf16 v[58:61], v[162:165], v[186:189], v[58:61]
	v_mfma_f32_16x16x32_bf16 v[50:53], v[154:157], v[194:197], v[50:53]
	v_mfma_f32_16x16x32_bf16 v[42:45], v[162:165], v[194:197], v[42:45]
	v_mfma_f32_16x16x32_bf16 v[34:37], v[154:157], v[202:205], v[34:37]
	v_mfma_f32_16x16x32_bf16 v[26:29], v[162:165], v[202:205], v[26:29]
	v_mfma_f32_16x16x32_bf16 v[18:21], v[154:157], v[214:217], v[18:21]
	v_mfma_f32_16x16x32_bf16 v[10:13], v[162:165], v[214:217], v[10:13]
	v_mfma_f32_16x16x32_bf16 v[54:57], v[170:173], v[186:189], v[54:57]
	v_mfma_f32_16x16x32_bf16 v[46:49], v[178:181], v[186:189], v[46:49]
	v_mfma_f32_16x16x32_bf16 v[38:41], v[170:173], v[194:197], v[38:41]
	v_mfma_f32_16x16x32_bf16 v[30:33], v[178:181], v[194:197], v[30:33]
	v_mfma_f32_16x16x32_bf16 v[22:25], v[170:173], v[202:205], v[22:25]
	v_mfma_f32_16x16x32_bf16 v[14:17], v[178:181], v[202:205], v[14:17]
	v_mfma_f32_16x16x32_bf16 v[6:9], v[170:173], v[214:217], v[6:9]
	v_mfma_f32_16x16x32_bf16 v[2:5], v[178:181], v[214:217], v[2:5]
	v_mfma_f32_16x16x32_bf16 v[62:65], v[158:161], v[190:193], v[62:65]
	v_mfma_f32_16x16x32_bf16 v[58:61], v[166:169], v[190:193], v[58:61]
	v_mfma_f32_16x16x32_bf16 v[50:53], v[158:161], v[198:201], v[50:53]
	v_mfma_f32_16x16x32_bf16 v[42:45], v[166:169], v[198:201], v[42:45]
	v_mfma_f32_16x16x32_bf16 v[34:37], v[158:161], v[210:213], v[34:37]
	v_mfma_f32_16x16x32_bf16 v[26:29], v[166:169], v[210:213], v[26:29]
	v_mfma_f32_16x16x32_bf16 v[18:21], v[158:161], v[218:221], v[18:21]
	v_mfma_f32_16x16x32_bf16 v[10:13], v[166:169], v[218:221], v[10:13]
	v_mfma_f32_16x16x32_bf16 v[54:57], v[174:177], v[190:193], v[54:57]
	v_mfma_f32_16x16x32_bf16 v[46:49], v[182:185], v[190:193], v[46:49]
	v_mfma_f32_16x16x32_bf16 v[38:41], v[174:177], v[198:201], v[38:41]
	v_mfma_f32_16x16x32_bf16 v[30:33], v[182:185], v[198:201], v[30:33]
	v_mfma_f32_16x16x32_bf16 v[22:25], v[174:177], v[210:213], v[22:25]
	v_mfma_f32_16x16x32_bf16 v[14:17], v[182:185], v[210:213], v[14:17]
	v_mfma_f32_16x16x32_bf16 v[6:9], v[174:177], v[218:221], v[6:9]
	v_mfma_f32_16x16x32_bf16 v[2:5], v[182:185], v[218:221], v[2:5]
	s_barrier
	s_add_i32 s97, s97, 2
	s_add_u32 s90, s90, 0x100
	s_addc_u32 s91, s91, 0
	s_add_u32 s89, s89, 0x100
	s_addc_u32 s96, s96, 0
	s_cmp_gt_u32 s97, 13
	s_cbranch_scc0 .LBB0_75
	s_and_b64 vcc, exec, s[46:47]
	s_cbranch_vccz .LBB0_78
	s_barrier

.LBB0_98:
	s_nop 0
	s_nop 0
	s_nop 0
	s_nop 0
	s_nop 0
	s_nop 0
	s_nop 0
	s_nop 0
	s_nop 0
	s_nop 0
	s_nop 0
	s_nop 0
	s_nop 0
	s_nop 0
	s_branch .LBB0_144
